# attn KV ring fill: all 9 row loads in flight before LDS writes
# baseline (speedup 1.0000x reference)
; #define LAS __attribute__((address_space(3)))
; __device__ __forceinline__ void attn_block(const f16* __restrict__ Q, const f16* __restrict__ Kb, const f16* __restrict__ VT, f16* __restrict__ ATT, const float* __restrict__ rpb_h,
;                                            LAS unsigned char* lds, int b, int h, int rc, int tid, int wave, int lane) {
;     ...
;     const int r0 = 8 * rc, srow = tid >> 3, sch = tid & 7;
;     const f16* ksrc = Kb + (size_t)(b * SEQ + srow) * DA + h * HD + sch * 8;
;     const f16* vsrc = VT + (size_t)(h * HD + srow) * VT_PITCH + b * SEQ + sch * 8;
;     const unsigned sdst = (unsigned)(srow * 128 + ((sch ^ ((srow >> 1) & 7)) * 16));
;     const int jlo = attn_rs(r0), jhi = attn_rs(r0 + 1) + 8;
;     for (int j = jlo; j < jhi; ++j) {
;         const u32x4 kk = *(const u32x4*)(ksrc + (size_t)j * GW * DA), vv = *(const u32x4*)(vsrc + j * GW); const int slot = (j % 9) * 16384;
;         *(LAS u32x4*)(lds + slot + sdst) = kk; *(LAS u32x4*)(lds + slot + 8192 + sdst) = vv; }
;     __syncthreads();
.LBB0_645:
	v_readfirstlane_b32 s99, v6
	global_load_dwordx4 v[8:11], v[4:5], off
	global_load_dwordx4 v[12:15], v[2:3], off
	v_lshl_add_u64 v[4:5], v[4:5], 0, s[38:39]
	v_lshl_add_u64 v[2:3], v[2:3], 0, s[40:41]
	global_load_dwordx4 v[172:175], v[4:5], off
	global_load_dwordx4 v[176:179], v[2:3], off
	v_lshl_add_u64 v[4:5], v[4:5], 0, s[38:39]
	v_lshl_add_u64 v[2:3], v[2:3], 0, s[40:41]
	global_load_dwordx4 v[180:183], v[4:5], off
	global_load_dwordx4 v[184:187], v[2:3], off
	v_lshl_add_u64 v[4:5], v[4:5], 0, s[38:39]
	v_lshl_add_u64 v[2:3], v[2:3], 0, s[40:41]
	global_load_dwordx4 v[188:191], v[4:5], off
	global_load_dwordx4 v[192:195], v[2:3], off
	v_lshl_add_u64 v[4:5], v[4:5], 0, s[38:39]
	v_lshl_add_u64 v[2:3], v[2:3], 0, s[40:41]
	global_load_dwordx4 v[196:199], v[4:5], off
	global_load_dwordx4 v[200:203], v[2:3], off
	v_lshl_add_u64 v[4:5], v[4:5], 0, s[38:39]
	v_lshl_add_u64 v[2:3], v[2:3], 0, s[40:41]
	global_load_dwordx4 v[204:207], v[4:5], off
	global_load_dwordx4 v[208:211], v[2:3], off
	v_lshl_add_u64 v[4:5], v[4:5], 0, s[38:39]
	v_lshl_add_u64 v[2:3], v[2:3], 0, s[40:41]
	global_load_dwordx4 v[234:237], v[4:5], off
	global_load_dwordx4 v[238:241], v[2:3], off
	v_lshl_add_u64 v[4:5], v[4:5], 0, s[38:39]
	v_lshl_add_u64 v[2:3], v[2:3], 0, s[40:41]
	global_load_dwordx4 v[242:245], v[4:5], off
	global_load_dwordx4 v[246:249], v[2:3], off
	v_lshl_add_u64 v[4:5], v[4:5], 0, s[38:39]
	v_lshl_add_u64 v[2:3], v[2:3], 0, s[40:41]
	global_load_dwordx4 v[212:215], v[4:5], off
	s_nop 0
	global_load_dwordx4 v[4:7], v[2:3], off
	s_mul_i32 s98, s13, 57
	s_bfe_u32 s98, s98, 0x70009
	s_mul_i32 s98, s98, 9
	s_sub_i32 s98, s13, s98
	s_and_b32 s98, s98, 0xff
	s_add_i32 s13, s13, 8
	s_waitcnt vmcnt(16)
	v_lshl_add_u32 v1, s98, 14, v103
	ds_write_b128 v1, v[8:11]
	ds_write_b128 v1, v[12:15] offset:8192
	s_add_i32 s98, s98, 1
	s_cmp_eq_u32 s98, 9
	s_cselect_b32 s98, 0, s98
	s_waitcnt vmcnt(14)
	v_lshl_add_u32 v1, s98, 14, v103
	ds_write_b128 v1, v[172:175]
	ds_write_b128 v1, v[176:179] offset:8192
	s_add_i32 s98, s98, 1
	s_cmp_eq_u32 s98, 9
	s_cselect_b32 s98, 0, s98
	s_waitcnt vmcnt(12)
	v_lshl_add_u32 v1, s98, 14, v103
	ds_write_b128 v1, v[180:183]
	ds_write_b128 v1, v[184:187] offset:8192
	s_add_i32 s98, s98, 1
	s_cmp_eq_u32 s98, 9
	s_cselect_b32 s98, 0, s98
	s_waitcnt vmcnt(10)
	v_lshl_add_u32 v1, s98, 14, v103
	ds_write_b128 v1, v[188:191]
	ds_write_b128 v1, v[192:195] offset:8192
	s_add_i32 s98, s98, 1
	s_cmp_eq_u32 s98, 9
	s_cselect_b32 s98, 0, s98
	s_waitcnt vmcnt(8)
	v_lshl_add_u32 v1, s98, 14, v103
	ds_write_b128 v1, v[196:199]
	ds_write_b128 v1, v[200:203] offset:8192
	s_add_i32 s98, s98, 1
	s_cmp_eq_u32 s98, 9
	s_cselect_b32 s98, 0, s98
	s_waitcnt vmcnt(6)
	v_lshl_add_u32 v1, s98, 14, v103
	ds_write_b128 v1, v[204:207]
	ds_write_b128 v1, v[208:211] offset:8192
	s_add_i32 s98, s98, 1
	s_cmp_eq_u32 s98, 9
	s_cselect_b32 s98, 0, s98
	s_waitcnt vmcnt(4)
	v_lshl_add_u32 v1, s98, 14, v103
	ds_write_b128 v1, v[234:237]
	ds_write_b128 v1, v[238:241] offset:8192
	s_add_i32 s98, s98, 1
	s_cmp_eq_u32 s98, 9
	s_cselect_b32 s98, 0, s98
	s_waitcnt vmcnt(2)
	v_lshl_add_u32 v1, s98, 14, v103
	ds_write_b128 v1, v[242:245]
	ds_write_b128 v1, v[246:249] offset:8192
	s_add_i32 s98, s98, 1
	s_cmp_eq_u32 s98, 9
	s_cselect_b32 s98, 0, s98
	s_cmp_lt_u32 s13, s99
	s_cbranch_scc0 .Lfill_done
	s_waitcnt vmcnt(0)
	v_lshl_add_u32 v1, s98, 14, v103
	ds_write_b128 v1, v[212:215]
	ds_write_b128 v1, v[4:7] offset:8192
.Lfill_done:
.LBB0_646:
	s_lshl_b32 s3, s23, 6
	s_and_b32 s16, s3, 0xfffff800
	v_add_u32_e32 v2, s16, v81
	v_ashrrev_i32_e32 v3, 31, v2
	v_readlane_b32 s26, v252, 11
	s_lshl_b32 s96, s24, 7
	v_ashrrev_i32_e32 v1, 31, v0
	v_readlane_b32 s24, v252, 7
	v_lshlrev_b64 v[2:3], 10, v[2:3]
	v_readlane_b32 s27, v252, 12
	v_lshlrev_b64 v[0:1], 15, v[0:1]
	v_readlane_b32 s25, v252, 8
	v_lshl_add_u64 v[2:3], s[26:27], 0, v[2:3]
	s_ashr_i32 s17, s16, 31
	v_lshl_add_u64 v[0:1], s[24:25], 0, v[0:1]
	v_lshl_add_u64 v[2:3], v[2:3], 0, s[96:97]
	v_lshl_add_u64 v[0:1], s[16:17], 1, v[0:1]
	s_add_i32 s12, s12, s2
	s_add_i32 s15, s18, s14
	v_lshl_add_u64 v[66:67], v[2:3], 0, v[32:33]
	v_lshl_add_u64 v[68:69], v[0:1], 0, v[32:33]
	v_add_u32_e32 v72, s12, v105
	s_sub_i32 s16, s20, s14
	v_lshl_add_u64 v[74:75], v[58:59], 0, s[96:97]
	v_lshl_add_u64 v[76:77], v[60:61], 0, s[96:97]
	s_mov_b32 s17, 0
	s_mov_b32 s24, s15
	s_waitcnt vmcnt(0) lgkmcnt(0)
	s_barrier
	s_branch .LBB0_648

; __global__ void __launch_bounds__(NTHREADS, 2) mk_fwd(Args args) {
	.amdhsa_kernel _Z6mk_fwd4Args
		.amdhsa_group_segment_fixed_size 0
		.amdhsa_private_segment_fixed_size 0
		.amdhsa_kernarg_size 448
		.amdhsa_user_sgpr_count 2
		.amdhsa_user_sgpr_dispatch_ptr 0
		.amdhsa_user_sgpr_queue_ptr 0
		.amdhsa_user_sgpr_kernarg_segment_ptr 1
		.amdhsa_user_sgpr_dispatch_id 0
		.amdhsa_user_sgpr_kernarg_preload_length 0
		.amdhsa_user_sgpr_kernarg_preload_offset 0
		.amdhsa_user_sgpr_private_segment_size 0
		.amdhsa_uses_dynamic_stack 0
		.amdhsa_enable_private_segment 0
		.amdhsa_system_sgpr_workgroup_id_x 1
		.amdhsa_system_sgpr_workgroup_id_y 0
		.amdhsa_system_sgpr_workgroup_id_z 0
		.amdhsa_system_sgpr_workgroup_info 0
		.amdhsa_system_vgpr_workitem_id 0
		.amdhsa_next_free_vgpr 256
		.amdhsa_next_free_sgpr 102
		.amdhsa_accum_offset 256
		.amdhsa_reserve_vcc 1
		.amdhsa_float_round_mode_32 0
		.amdhsa_float_round_mode_16_64 0
		.amdhsa_float_denorm_mode_32 3
		.amdhsa_float_denorm_mode_16_64 3
		.amdhsa_dx10_clamp 1
		.amdhsa_ieee_mode 1
		.amdhsa_fp16_overflow 0
		.amdhsa_tg_split 0
		.amdhsa_exception_fp_ieee_invalid_op 0
		.amdhsa_exception_fp_denorm_src 0
		.amdhsa_exception_fp_ieee_div_zero 0
		.amdhsa_exception_fp_ieee_overflow 0
		.amdhsa_exception_fp_ieee_underflow 0
		.amdhsa_exception_fp_ieee_inexact 0
		.amdhsa_exception_int_div_zero 0
	.end_amdhsa_kernel

; __global__ void __launch_bounds__(NTHREADS, 2) mk_fwd(Args args) {
amdhsa.kernels:
  - .agpr_count:     0
    .args:
      - .offset:         0
        .size:           192
        .value_kind:     by_value
      - .offset:         192
        .size:           4
        .value_kind:     hidden_block_count_x
      - .offset:         196
        .size:           4
        .value_kind:     hidden_block_count_y
      - .offset:         200
        .size:           4
        .value_kind:     hidden_block_count_z
      - .offset:         204
        .size:           2
        .value_kind:     hidden_group_size_x
      - .offset:         206
        .size:           2
        .value_kind:     hidden_group_size_y
      - .offset:         208
        .size:           2
        .value_kind:     hidden_group_size_z
      - .offset:         210
        .size:           2
        .value_kind:     hidden_remainder_x
      - .offset:         212
        .size:           2
        .value_kind:     hidden_remainder_y
      - .offset:         214
        .size:           2
        .value_kind:     hidden_remainder_z
      - .offset:         232
        .size:           8
        .value_kind:     hidden_global_offset_x
      - .offset:         240
        .size:           8
        .value_kind:     hidden_global_offset_y
      - .offset:         248
        .size:           8
        .value_kind:     hidden_global_offset_z
      - .offset:         256
        .size:           2
        .value_kind:     hidden_grid_dims
      - .offset:         312
        .size:           4
        .value_kind:     hidden_dynamic_lds_size
    .group_segment_fixed_size: 0
    .kernarg_segment_align: 8
    .kernarg_segment_size: 448
    .language:       OpenCL C
    .language_version:
      - 2
      - 0
    .max_flat_workgroup_size: 512
    .name:           _Z6mk_fwd4Args
    .private_segment_fixed_size: 0
    .sgpr_count:     108
    .sgpr_spill_count: 289
    .symbol:         _Z6mk_fwd4Args.kd
    .uniform_work_group_size: 1
    .uses_dynamic_stack: false
    .vgpr_count:     256
    .vgpr_spill_count: 0
    .wavefront_size: 64
